# attention unit: late rope-gain load pair hoisted into its batch; 16 row-sum LDS reads of the O-normalize step issued up front
# speedup vs baseline: 1.0017x; 1.0017x over previous
; __device__ __forceinline__ bf16_t f2bf(float f) { return (bf16_t)(cvt_pk_bf16(f, 0.f) & 0xffffu); }
; __device__ __forceinline__ int crow(int r, int hi) { return (r & 3) + 8 * (r >> 2) + 4 * hi; }
; __device__ __forceinline__ void attn_unit_dma(const bf16_t* __restrict__ Qb, const bf16_t* __restrict__ Kh, const bf16_t* __restrict__ Vh, int seq, char* lds, LAS unsigned char* ldsl, ...
;     ...
;   if (hi == 0) li_l[r32] = l_reg; asm volatile("s_waitcnt vmcnt(0) lgkmcnt(0)" ::: "memory");
;   __syncthreads();
;   {
;     constexpr int RS = 272;
;     int tid_e = threadIdx.x; asm volatile("" : "+v"(tid_e));
;     const int wid = tid_e >> 6, lane = tid_e & 63, r32 = lane & 31, hi = lane >> 5;
;     char* Ost = lds + wid * (32 * RS);
; #pragma unroll
;     for (int r = 0; r < 16; ++r) { const int rw = crow(r, hi); const float rl = __builtin_amdgcn_rcpf(li_l[rw]);
; #pragma unroll
;       for (int d0 = 0; d0 < 4; ++d0) *(bf16_t*)(Ost + rw * RS + (d0 * 32 + r32) * 2) = f2bf(o[d0][r] * rl); }
.LBB0_813:
	s_or_b64 exec, exec, s[6:7]
	v_mov_b32_e32 v66, v0
	s_waitcnt vmcnt(0) lgkmcnt(0)
	s_waitcnt vmcnt(0) lgkmcnt(0)
	s_barrier
	s_movk_i32 s6, 0x2200
	v_lshrrev_b32_e32 v67, 3, v66
	v_and_b32_e32 v67, 4, v67
	v_lshl_add_u32 v68, v67, 2, s10
	ds_read_b32 v69, v68
	ds_read_b32 v74, v68 offset:4
	ds_read_b32 v75, v68 offset:8
	ds_read_b32 v76, v68 offset:12
	ds_read_b32 v77, v68 offset:32
	ds_read_b32 v78, v68 offset:36
	ds_read_b32 v79, v68 offset:40
	ds_read_b32 v80, v68 offset:44
	ds_read_b32 v81, v68 offset:64
	ds_read_b32 v82, v68 offset:68
	ds_read_b32 v83, v68 offset:72
	ds_read_b32 v84, v68 offset:76
	ds_read_b32 v85, v68 offset:96
	ds_read_b32 v86, v68 offset:100
	ds_read_b32 v87, v68 offset:104
	ds_read_b32 v88, v68 offset:108
	v_ashrrev_i32_e32 v70, 6, v66
	v_mul_lo_u32 v71, v70, s6
	v_lshlrev_b32_e32 v72, 1, v66
	v_add_u32_e32 v71, 0, v71
	s_waitcnt lgkmcnt(0)
	v_rcp_f32_e32 v69, v69
	v_and_b32_e32 v72, 62, v72
	v_mul_u32_u24_e32 v67, 0x110, v67
	v_add3_u32 v67, v71, v67, v72
	v_mul_f32_e32 v2, v2, v69
	v_cvt_pk_bf16_f32 v2, v2, v115
	ds_write_b16 v67, v2
	v_mul_f32_e32 v2, v18, v69
	v_cvt_pk_bf16_f32 v2, v2, v115
	ds_write_b16 v67, v2 offset:64
	v_mul_f32_e32 v2, v34, v69
	v_cvt_pk_bf16_f32 v2, v2, v115
	ds_write_b16 v67, v2 offset:128
	v_mul_f32_e32 v2, v50, v69
	v_cvt_pk_bf16_f32 v2, v2, v115
	v_mov_b32_e32 v18, v74
	ds_write_b16 v67, v2 offset:192
	s_mul_i32 s6, s21, 0xa400
	s_mul_hi_u32 s7, s20, 0xa400
	s_add_i32 s7, s7, s6
	v_rcp_f32_e32 v18, v18
	s_mul_i32 s6, s20, 0xa400
	s_add_u32 s6, s77, s6
	s_addc_u32 s7, s62, s7
	v_mul_f32_e32 v2, v3, v18
	v_cvt_pk_bf16_f32 v2, v2, v115
	ds_write_b16 v67, v2 offset:272
	v_mul_f32_e32 v2, v19, v18
	v_cvt_pk_bf16_f32 v2, v2, v115
	ds_write_b16 v67, v2 offset:336
	v_mul_f32_e32 v2, v35, v18
	v_cvt_pk_bf16_f32 v2, v2, v115
	ds_write_b16 v67, v2 offset:400
	v_mul_f32_e32 v2, v51, v18
	v_cvt_pk_bf16_f32 v2, v2, v115
	v_mov_b32_e32 v3, v75
	ds_write_b16 v67, v2 offset:464
	s_lshl_b32 s10, s36, 8
	s_add_u32 s6, s6, s10
	s_addc_u32 s7, s7, 0
	v_rcp_f32_e32 v3, v3
	s_nop 0
	v_mul_f32_e32 v2, v4, v3
	v_cvt_pk_bf16_f32 v2, v2, v115
	ds_write_b16 v67, v2 offset:544
	v_mul_f32_e32 v2, v20, v3
	v_cvt_pk_bf16_f32 v2, v2, v115
	ds_write_b16 v67, v2 offset:608
	v_mul_f32_e32 v2, v36, v3
	v_cvt_pk_bf16_f32 v2, v2, v115
	ds_write_b16 v67, v2 offset:672
	v_mul_f32_e32 v2, v52, v3
	v_cvt_pk_bf16_f32 v2, v2, v115
	v_mov_b32_e32 v3, v76
	ds_write_b16 v67, v2 offset:736
	v_rcp_f32_e32 v3, v3
	s_nop 0
	v_mul_f32_e32 v2, v5, v3
	v_cvt_pk_bf16_f32 v2, v2, v115
	ds_write_b16 v67, v2 offset:816
	v_mul_f32_e32 v2, v21, v3
	v_cvt_pk_bf16_f32 v2, v2, v115
	ds_write_b16 v67, v2 offset:880
	v_mul_f32_e32 v2, v37, v3
	v_cvt_pk_bf16_f32 v2, v2, v115
	ds_write_b16 v67, v2 offset:944
	v_mul_f32_e32 v2, v53, v3
	v_cvt_pk_bf16_f32 v2, v2, v115
	v_mov_b32_e32 v3, v77
	ds_write_b16 v67, v2 offset:1008
	v_bfe_u32 v5, v66, 4, 2
	v_lshl_or_b32 v4, v70, 5, v5
	v_mul_u32_u24_e32 v5, 0x110, v5
	v_rcp_f32_e32 v3, v3
	s_nop 0
	v_mul_f32_e32 v2, v6, v3
	v_cvt_pk_bf16_f32 v2, v2, v115
	ds_write_b16 v67, v2 offset:2176
	v_mul_f32_e32 v2, v22, v3
	v_cvt_pk_bf16_f32 v2, v2, v115
	ds_write_b16 v67, v2 offset:2240
	v_mul_f32_e32 v2, v38, v3
	v_cvt_pk_bf16_f32 v2, v2, v115
	ds_write_b16 v67, v2 offset:2304
	v_mul_f32_e32 v2, v54, v3
	v_cvt_pk_bf16_f32 v2, v2, v115
	v_mov_b32_e32 v3, v78
	ds_write_b16 v67, v2 offset:2368
	v_or_b32_e32 v22, 4, v4
	v_rcp_f32_e32 v3, v3
	s_nop 0
	v_mul_f32_e32 v2, v7, v3
	v_cvt_pk_bf16_f32 v2, v2, v115
	ds_write_b16 v67, v2 offset:2448
	v_mul_f32_e32 v2, v23, v3
	v_cvt_pk_bf16_f32 v2, v2, v115
	ds_write_b16 v67, v2 offset:2512
	v_mul_f32_e32 v2, v39, v3
	v_cvt_pk_bf16_f32 v2, v2, v115
	ds_write_b16 v67, v2 offset:2576
	v_mul_f32_e32 v2, v55, v3
	v_cvt_pk_bf16_f32 v2, v2, v115
	v_mov_b32_e32 v3, v79
	ds_write_b16 v67, v2 offset:2640
	v_rcp_f32_e32 v3, v3
	s_nop 0
	v_mul_f32_e32 v2, v8, v3
	v_cvt_pk_bf16_f32 v2, v2, v115
	ds_write_b16 v67, v2 offset:2720
	v_mul_f32_e32 v2, v24, v3
	v_cvt_pk_bf16_f32 v2, v2, v115
	ds_write_b16 v67, v2 offset:2784
	v_mul_f32_e32 v2, v40, v3
	v_cvt_pk_bf16_f32 v2, v2, v115
	ds_write_b16 v67, v2 offset:2848
	v_mul_f32_e32 v2, v56, v3
	v_cvt_pk_bf16_f32 v2, v2, v115
	v_mov_b32_e32 v3, v80
	ds_write_b16 v67, v2 offset:2912
	v_rcp_f32_e32 v3, v3
	s_nop 0
	v_mul_f32_e32 v2, v9, v3
	v_cvt_pk_bf16_f32 v2, v2, v115
	ds_write_b16 v67, v2 offset:2992
	v_mul_f32_e32 v2, v25, v3
	v_cvt_pk_bf16_f32 v2, v2, v115
	ds_write_b16 v67, v2 offset:3056
	v_mul_f32_e32 v2, v41, v3
	v_cvt_pk_bf16_f32 v2, v2, v115
	ds_write_b16 v67, v2 offset:3120
	v_mul_f32_e32 v2, v57, v3
	v_cvt_pk_bf16_f32 v2, v2, v115
	v_mov_b32_e32 v3, v81
	ds_write_b16 v67, v2 offset:3184
	v_rcp_f32_e32 v3, v3
	s_nop 0
	v_mul_f32_e32 v2, v10, v3
	v_cvt_pk_bf16_f32 v2, v2, v115
	ds_write_b16 v67, v2 offset:4352
	v_mul_f32_e32 v2, v26, v3
	v_cvt_pk_bf16_f32 v2, v2, v115
	ds_write_b16 v67, v2 offset:4416
	v_mul_f32_e32 v2, v42, v3
	v_cvt_pk_bf16_f32 v2, v2, v115
	ds_write_b16 v67, v2 offset:4480
	v_mul_f32_e32 v2, v58, v3
	v_cvt_pk_bf16_f32 v2, v2, v115
	v_mov_b32_e32 v3, v82
	ds_write_b16 v67, v2 offset:4544
	v_rcp_f32_e32 v3, v3
	s_nop 0
	v_mul_f32_e32 v2, v11, v3
	v_cvt_pk_bf16_f32 v2, v2, v115
	ds_write_b16 v67, v2 offset:4624
	v_mul_f32_e32 v2, v27, v3
	v_cvt_pk_bf16_f32 v2, v2, v115
	ds_write_b16 v67, v2 offset:4688
	v_mul_f32_e32 v2, v43, v3
	v_cvt_pk_bf16_f32 v2, v2, v115
	ds_write_b16 v67, v2 offset:4752
	v_mul_f32_e32 v2, v59, v3
	v_cvt_pk_bf16_f32 v2, v2, v115
	v_mov_b32_e32 v3, v83
	ds_write_b16 v67, v2 offset:4816
	v_rcp_f32_e32 v3, v3
	s_nop 0
	v_mul_f32_e32 v2, v12, v3
	v_cvt_pk_bf16_f32 v2, v2, v115
; __device__ __forceinline__ float bf_lo(unsigned w) { return __uint_as_float(w << 16); }
; __device__ __forceinline__ float bf_hi(unsigned w) { return __uint_as_float(w & 0xffff0000u); }
; __device__ __forceinline__ unsigned cvt_pk_bf16(float lo, float hi) { unsigned r; asm volatile("v_cvt_pk_bf16_f32 %0, %1, %2" : "=v"(r) : "v"(lo), "v"(hi)); return r; }
; __device__ __forceinline__ bf16_t f2bf(float f) { return (bf16_t)(cvt_pk_bf16(f, 0.f) & 0xffffu); }
; __device__ __forceinline__ int crow(int r, int hi) { return (r & 3) + 8 * (r >> 2) + 4 * hi; }
; __device__ __forceinline__ void attn_unit_dma(const bf16_t* __restrict__ Qb, const bf16_t* __restrict__ Kh, const bf16_t* __restrict__ Vh, int seq, char* lds, LAS unsigned char* ldsl, ...
;     ...
;     for (int r = 0; r < 16; ++r) { const int rw = crow(r, hi); const float rl = __builtin_amdgcn_rcpf(li_l[rw]);
; #pragma unroll
;       for (int d0 = 0; d0 < 4; ++d0) *(bf16_t*)(Ost + rw * RS + (d0 * 32 + r32) * 2) = f2bf(o[d0][r] * rl); }
;     asm volatile("s_waitcnt lgkmcnt(0)" ::: "memory");
; #pragma unroll
;     for (int i = 0; i < 8; ++i) { const int q = lane + 64 * i, row = q >> 4, cc = q & 15; const long orow = wid * QBLK + row;
;       const u32x4 ov = *(const u32x4*)(Ost + row * RS + cc * 16); const u32x4 gv = *(const u32x4*)(gate + orow * NZ + cc * 8);
;       u32x4 w; w.x = cvt_pk_bf16(bf_lo(ov.x) * bf_lo(gv.x), bf_hi(ov.x) * bf_hi(gv.x)); w.y = cvt_pk_bf16(bf_lo(ov.y) * bf_lo(gv.y), bf_hi(ov.y) * bf_hi(gv.y));
;       w.z = cvt_pk_bf16(bf_lo(ov.z) * bf_lo(gv.z), bf_hi(ov.z) * bf_hi(gv.z)); w.w = cvt_pk_bf16(bf_lo(ov.w) * bf_lo(gv.w), bf_hi(ov.w) * bf_hi(gv.w));
;       *(u32x4*)(Yo + orow * 4096 + cc * 8) = w; }
	ds_write_b16 v67, v2 offset:4896
	v_mul_f32_e32 v2, v28, v3
	v_cvt_pk_bf16_f32 v2, v2, v115
	ds_write_b16 v67, v2 offset:4960
	v_mul_f32_e32 v2, v44, v3
	v_cvt_pk_bf16_f32 v2, v2, v115
	ds_write_b16 v67, v2 offset:5024
	v_mul_f32_e32 v2, v60, v3
	v_cvt_pk_bf16_f32 v2, v2, v115
	v_mov_b32_e32 v3, v84
	ds_write_b16 v67, v2 offset:5088
	v_rcp_f32_e32 v3, v3
	s_nop 0
	v_mul_f32_e32 v2, v13, v3
	v_cvt_pk_bf16_f32 v2, v2, v115
	ds_write_b16 v67, v2 offset:5168
	v_mul_f32_e32 v2, v29, v3
	v_cvt_pk_bf16_f32 v2, v2, v115
	ds_write_b16 v67, v2 offset:5232
	v_mul_f32_e32 v2, v45, v3
	v_cvt_pk_bf16_f32 v2, v2, v115
	ds_write_b16 v67, v2 offset:5296
	v_mul_f32_e32 v2, v61, v3
	v_cvt_pk_bf16_f32 v2, v2, v115
	v_mov_b32_e32 v3, v85
	ds_write_b16 v67, v2 offset:5360
	v_rcp_f32_e32 v3, v3
	s_nop 0
	v_mul_f32_e32 v2, v14, v3
	v_cvt_pk_bf16_f32 v2, v2, v115
	ds_write_b16 v67, v2 offset:6528
	v_mul_f32_e32 v2, v30, v3
	v_cvt_pk_bf16_f32 v2, v2, v115
	ds_write_b16 v67, v2 offset:6592
	v_mul_f32_e32 v2, v46, v3
	v_cvt_pk_bf16_f32 v2, v2, v115
	ds_write_b16 v67, v2 offset:6656
	v_mul_f32_e32 v2, v62, v3
	v_cvt_pk_bf16_f32 v2, v2, v115
	v_mov_b32_e32 v3, v86
	ds_write_b16 v67, v2 offset:6720
	v_rcp_f32_e32 v3, v3
	s_nop 0
	v_mul_f32_e32 v2, v15, v3
	v_cvt_pk_bf16_f32 v2, v2, v115
	ds_write_b16 v67, v2 offset:6800
	v_mul_f32_e32 v2, v31, v3
	v_cvt_pk_bf16_f32 v2, v2, v115
	ds_write_b16 v67, v2 offset:6864
	v_mul_f32_e32 v2, v47, v3
	v_cvt_pk_bf16_f32 v2, v2, v115
	ds_write_b16 v67, v2 offset:6928
	v_mul_f32_e32 v2, v63, v3
	v_cvt_pk_bf16_f32 v2, v2, v115
	v_mov_b32_e32 v3, v87
	ds_write_b16 v67, v2 offset:6992
	v_rcp_f32_e32 v3, v3
	s_nop 0
	v_mul_f32_e32 v2, v16, v3
	v_cvt_pk_bf16_f32 v2, v2, v115
	ds_write_b16 v67, v2 offset:7072
	v_mul_f32_e32 v2, v32, v3
	v_cvt_pk_bf16_f32 v2, v2, v115
	ds_write_b16 v67, v2 offset:7136
	v_mul_f32_e32 v2, v48, v3
	v_cvt_pk_bf16_f32 v2, v2, v115
	ds_write_b16 v67, v2 offset:7200
	v_mul_f32_e32 v2, v64, v3
	v_cvt_pk_bf16_f32 v2, v2, v115
	v_mov_b32_e32 v3, v88
	ds_write_b16 v67, v2 offset:7264
	v_rcp_f32_e32 v3, v3
	s_nop 0
	v_mul_f32_e32 v2, v17, v3
	v_cvt_pk_bf16_f32 v2, v2, v115
	ds_write_b16 v67, v2 offset:7344
	v_mul_f32_e32 v2, v33, v3
	v_cvt_pk_bf16_f32 v2, v2, v115
	ds_write_b16 v67, v2 offset:7408
	v_mul_f32_e32 v2, v49, v3
	v_cvt_pk_bf16_f32 v2, v2, v115
	ds_write_b16 v67, v2 offset:7472
	v_mul_f32_e32 v2, v65, v3
	v_cvt_pk_bf16_f32 v2, v2, v115
	ds_write_b16 v67, v2 offset:7536
	v_lshlrev_b32_e32 v2, 4, v66
	v_and_b32_e32 v114, 0xf0, v2
	v_lshl_add_u64 v[2:3], s[6:7], 0, v[114:115]
	s_mov_b64 s[6:7], 0x1c00
	v_lshl_add_u64 v[2:3], v[2:3], 0, s[6:7]
	s_waitcnt lgkmcnt(0)
	v_mad_i64_i32 v[6:7], s[6:7], v4, s42, v[2:3]
	s_mov_b64 s[98:99], 0x29000
	global_load_dwordx4 v[30:33], v[6:7], off
	v_lshl_add_u64 v[62:63], v[6:7], 0, s[98:99]
	global_load_dwordx4 v[34:37], v[62:63], off
	v_lshl_add_u64 v[62:63], v[62:63], 0, s[98:99]
	global_load_dwordx4 v[38:41], v[62:63], off
	v_lshl_add_u64 v[62:63], v[62:63], 0, s[98:99]
	global_load_dwordx4 v[42:45], v[62:63], off
	v_lshl_add_u64 v[62:63], v[62:63], 0, s[98:99]
	global_load_dwordx4 v[46:49], v[62:63], off
	v_lshl_add_u64 v[62:63], v[62:63], 0, s[98:99]
	global_load_dwordx4 v[50:53], v[62:63], off
	v_lshl_add_u64 v[62:63], v[62:63], 0, s[98:99]
	global_load_dwordx4 v[54:57], v[62:63], off
	v_lshl_add_u64 v[62:63], v[62:63], 0, s[98:99]
	global_load_dwordx4 v[58:61], v[62:63], off
	v_add3_u32 v8, v71, v114, v5
	ds_read_b128 v[14:17], v8
	v_mad_i64_i32 v[6:7], s[6:7], v22, s42, v[2:3]
	s_lshl_b64 s[6:7], s[20:21], 13
	s_add_u32 s6, s78, s6
	s_waitcnt lgkmcnt(0)
	v_lshlrev_b32_e32 v5, 16, v14
	v_and_b32_e32 v9, 0xffff0000, v14
	v_lshlrev_b32_e32 v14, 16, v15
	v_and_b32_e32 v15, 0xffff0000, v15
	v_lshlrev_b32_e32 v18, 16, v16
	v_and_b32_e32 v16, 0xffff0000, v16
	v_lshlrev_b32_e32 v19, 16, v17
	v_and_b32_e32 v17, 0xffff0000, v17
	s_addc_u32 s7, s79, s7
	s_add_u32 s6, s6, s10
	s_addc_u32 s7, s7, 0
	s_add_i32 s12, s12, 1
	s_waitcnt vmcnt(7)
	v_mov_b32_e32 v10, v30
	v_mov_b32_e32 v11, v31
	v_mov_b32_e32 v12, v32
	v_mov_b32_e32 v13, v33
	v_lshlrev_b32_e32 v21, 16, v11
	v_and_b32_e32 v11, 0xffff0000, v11
	v_lshlrev_b32_e32 v23, 16, v12
	v_and_b32_e32 v12, 0xffff0000, v12
	v_lshlrev_b32_e32 v24, 16, v13
	v_and_b32_e32 v13, 0xffff0000, v13
	v_lshlrev_b32_e32 v20, 16, v10
	v_and_b32_e32 v10, 0xffff0000, v10
	v_mul_f32_e32 v14, v21, v14
	v_mul_f32_e32 v11, v11, v15
	v_mul_f32_e32 v15, v23, v18
	v_mul_f32_e32 v12, v12, v16
	v_mul_f32_e32 v16, v24, v19
	v_mul_f32_e32 v13, v13, v17
	v_mul_f32_e32 v5, v20, v5
	v_mul_f32_e32 v9, v10, v9
	v_cvt_pk_bf16_f32 v10, v5, v9
	v_cvt_pk_bf16_f32 v11, v14, v11
	v_cvt_pk_bf16_f32 v12, v15, v12
	v_cvt_pk_bf16_f32 v13, v16, v13
	ds_read_b128 v[18:21], v8 offset:1088
	v_ashrrev_i32_e32 v5, 31, v4
	v_lshlrev_b64 v[26:27], 13, v[4:5]
	v_lshl_add_u64 v[6:7], s[6:7], 0, v[114:115]
	v_lshl_add_u64 v[26:27], v[6:7], 0, v[26:27]
	v_or_b32_e32 v24, 8, v4
	global_store_dwordx4 v[26:27], v[10:13], off offset:2048
	s_waitcnt lgkmcnt(0)
	v_lshlrev_b32_e32 v5, 16, v18
	v_and_b32_e32 v9, 0xffff0000, v18
	v_lshlrev_b32_e32 v10, 16, v19
	v_and_b32_e32 v11, 0xffff0000, v19
	v_lshlrev_b32_e32 v12, 16, v20
	v_and_b32_e32 v13, 0xffff0000, v20
	v_lshlrev_b32_e32 v18, 16, v21
	v_and_b32_e32 v19, 0xffff0000, v21
	v_mad_i64_i32 v[28:29], s[10:11], v24, s42, v[2:3]
	v_or_b32_e32 v26, 12, v4
	v_ashrrev_i32_e32 v27, 31, v26
	s_waitcnt vmcnt(7)
; __device__ __forceinline__ float bf_lo(unsigned w) { return __uint_as_float(w << 16); }
; __device__ __forceinline__ float bf_hi(unsigned w) { return __uint_as_float(w & 0xffff0000u); }
; __device__ __forceinline__ unsigned cvt_pk_bf16(float lo, float hi) { unsigned r; asm volatile("v_cvt_pk_bf16_f32 %0, %1, %2" : "=v"(r) : "v"(lo), "v"(hi)); return r; }
; __device__ __forceinline__ void attn_unit_dma(const bf16_t* __restrict__ Qb, const bf16_t* __restrict__ Kh, const bf16_t* __restrict__ Vh, int seq, char* lds, LAS unsigned char* ldsl, ...
;     ...
;     for (int i = 0; i < 8; ++i) { const int q = lane + 64 * i, row = q >> 4, cc = q & 15; const long orow = wid * QBLK + row;
;       const u32x4 ov = *(const u32x4*)(Ost + row * RS + cc * 16); const u32x4 gv = *(const u32x4*)(gate + orow * NZ + cc * 8);
;       u32x4 w; w.x = cvt_pk_bf16(bf_lo(ov.x) * bf_lo(gv.x), bf_hi(ov.x) * bf_hi(gv.x)); w.y = cvt_pk_bf16(bf_lo(ov.y) * bf_lo(gv.y), bf_hi(ov.y) * bf_hi(gv.y));
;       w.z = cvt_pk_bf16(bf_lo(ov.z) * bf_lo(gv.z), bf_hi(ov.z) * bf_hi(gv.z)); w.w = cvt_pk_bf16(bf_lo(ov.w) * bf_lo(gv.w), bf_hi(ov.w) * bf_hi(gv.w));
;       *(u32x4*)(Yo + orow * 4096 + cc * 8) = w; }
	v_mov_b32_e32 v14, v34
	v_mov_b32_e32 v15, v35
	v_mov_b32_e32 v16, v36
	v_mov_b32_e32 v17, v37
	v_lshlrev_b32_e32 v20, 16, v14
	v_and_b32_e32 v14, 0xffff0000, v14
	v_lshlrev_b32_e32 v21, 16, v15
	v_and_b32_e32 v15, 0xffff0000, v15
	v_lshlrev_b32_e32 v23, 16, v16
	v_and_b32_e32 v16, 0xffff0000, v16
	v_lshlrev_b32_e32 v25, 16, v17
	v_and_b32_e32 v17, 0xffff0000, v17
	v_mul_f32_e32 v9, v14, v9
	v_mul_f32_e32 v14, v21, v10
	v_mul_f32_e32 v11, v15, v11
	v_mul_f32_e32 v12, v23, v12
	v_mul_f32_e32 v13, v16, v13
	v_mul_f32_e32 v15, v25, v18
	v_mul_f32_e32 v16, v17, v19
	v_mul_f32_e32 v5, v20, v5
	v_cvt_pk_bf16_f32 v10, v5, v9
	v_cvt_pk_bf16_f32 v11, v14, v11
	v_cvt_pk_bf16_f32 v12, v12, v13
	v_cvt_pk_bf16_f32 v13, v15, v16
	ds_read_b128 v[18:21], v8 offset:2176
	v_ashrrev_i32_e32 v23, 31, v22
	v_lshlrev_b64 v[22:23], 13, v[22:23]
	v_lshl_add_u64 v[22:23], v[6:7], 0, v[22:23]
	global_store_dwordx4 v[22:23], v[10:13], off offset:2048
	s_waitcnt lgkmcnt(0)
	v_lshlrev_b32_e32 v5, 16, v18
	v_and_b32_e32 v9, 0xffff0000, v18
	v_lshlrev_b32_e32 v10, 16, v19
	v_and_b32_e32 v11, 0xffff0000, v19
	v_lshlrev_b32_e32 v12, 16, v20
	v_and_b32_e32 v13, 0xffff0000, v20
	v_lshlrev_b32_e32 v18, 16, v21
	v_and_b32_e32 v19, 0xffff0000, v21
	v_mad_i64_i32 v[28:29], s[6:7], v26, s42, v[2:3]
	v_ashrrev_i32_e32 v25, 31, v24
	v_lshlrev_b64 v[24:25], 13, v[24:25]
	v_lshl_add_u64 v[24:25], v[6:7], 0, v[24:25]
	v_lshlrev_b64 v[26:27], 13, v[26:27]
	v_lshl_add_u64 v[26:27], v[6:7], 0, v[26:27]
	s_waitcnt vmcnt(7)
	v_mov_b32_e32 v14, v38
	v_mov_b32_e32 v15, v39
	v_mov_b32_e32 v16, v40
	v_mov_b32_e32 v17, v41
	v_lshlrev_b32_e32 v20, 16, v14
	v_and_b32_e32 v14, 0xffff0000, v14
	v_lshlrev_b32_e32 v21, 16, v15
	v_and_b32_e32 v15, 0xffff0000, v15
	v_lshlrev_b32_e32 v22, 16, v16
	v_and_b32_e32 v16, 0xffff0000, v16
	v_lshlrev_b32_e32 v23, 16, v17
	v_and_b32_e32 v17, 0xffff0000, v17
	v_mul_f32_e32 v9, v14, v9
	v_mul_f32_e32 v14, v21, v10
	v_mul_f32_e32 v11, v15, v11
	v_mul_f32_e32 v12, v22, v12
	v_mul_f32_e32 v13, v16, v13
	v_mul_f32_e32 v15, v23, v18
	v_mul_f32_e32 v16, v17, v19
	v_mul_f32_e32 v5, v20, v5
	v_cvt_pk_bf16_f32 v10, v5, v9
	v_cvt_pk_bf16_f32 v11, v14, v11
	v_cvt_pk_bf16_f32 v12, v12, v13
	v_cvt_pk_bf16_f32 v13, v15, v16
	ds_read_b128 v[18:21], v8 offset:3264
	v_or_b32_e32 v22, 16, v4
	global_store_dwordx4 v[24:25], v[10:13], off offset:2048
	v_mad_i64_i32 v[28:29], s[6:7], v22, s42, v[2:3]
	s_waitcnt lgkmcnt(0)
	v_lshlrev_b32_e32 v5, 16, v18
	v_and_b32_e32 v9, 0xffff0000, v18
	v_lshlrev_b32_e32 v10, 16, v19
	v_and_b32_e32 v11, 0xffff0000, v19
	v_lshlrev_b32_e32 v12, 16, v20
	v_and_b32_e32 v13, 0xffff0000, v20
	v_lshlrev_b32_e32 v18, 16, v21
	v_and_b32_e32 v19, 0xffff0000, v21
	s_waitcnt vmcnt(7)
	v_mov_b32_e32 v14, v42
	v_mov_b32_e32 v15, v43
	v_mov_b32_e32 v16, v44
	v_mov_b32_e32 v17, v45
	v_lshlrev_b32_e32 v20, 16, v14
	v_and_b32_e32 v14, 0xffff0000, v14
	v_lshlrev_b32_e32 v21, 16, v15
	v_and_b32_e32 v15, 0xffff0000, v15
	v_lshlrev_b32_e32 v23, 16, v16
	v_and_b32_e32 v16, 0xffff0000, v16
	v_lshlrev_b32_e32 v24, 16, v17
	v_and_b32_e32 v17, 0xffff0000, v17
	v_mul_f32_e32 v9, v14, v9
	v_mul_f32_e32 v14, v21, v10
	v_mul_f32_e32 v11, v15, v11
	v_mul_f32_e32 v12, v23, v12
	v_mul_f32_e32 v13, v16, v13
	v_mul_f32_e32 v15, v24, v18
	v_mul_f32_e32 v16, v17, v19
	v_mul_f32_e32 v5, v20, v5
	v_cvt_pk_bf16_f32 v10, v5, v9
	v_cvt_pk_bf16_f32 v11, v14, v11
	v_cvt_pk_bf16_f32 v12, v12, v13
	v_cvt_pk_bf16_f32 v13, v15, v16
	ds_read_b128 v[18:21], v8 offset:4352
	v_or_b32_e32 v24, 20, v4
	global_store_dwordx4 v[26:27], v[10:13], off offset:2048
	v_mad_i64_i32 v[28:29], s[6:7], v24, s42, v[2:3]
	s_waitcnt lgkmcnt(0)
	v_lshlrev_b32_e32 v5, 16, v18
	v_and_b32_e32 v9, 0xffff0000, v18
	v_lshlrev_b32_e32 v10, 16, v19
	v_and_b32_e32 v11, 0xffff0000, v19
	v_lshlrev_b32_e32 v12, 16, v20
	v_and_b32_e32 v13, 0xffff0000, v20
	v_lshlrev_b32_e32 v18, 16, v21
	v_and_b32_e32 v19, 0xffff0000, v21
	v_or_b32_e32 v26, 24, v4
	v_ashrrev_i32_e32 v27, 31, v26
	s_waitcnt vmcnt(7)
; __device__ __forceinline__ float bf_lo(unsigned w) { return __uint_as_float(w << 16); }
; __device__ __forceinline__ float bf_hi(unsigned w) { return __uint_as_float(w & 0xffff0000u); }
; __device__ __forceinline__ unsigned cvt_pk_bf16(float lo, float hi) { unsigned r; asm volatile("v_cvt_pk_bf16_f32 %0, %1, %2" : "=v"(r) : "v"(lo), "v"(hi)); return r; }
; __device__ __forceinline__ void attn_unit_dma(const bf16_t* __restrict__ Qb, const bf16_t* __restrict__ Kh, const bf16_t* __restrict__ Vh, int seq, char* lds, LAS unsigned char* ldsl, ...
;     ...
;     for (int i = 0; i < 8; ++i) { const int q = lane + 64 * i, row = q >> 4, cc = q & 15; const long orow = wid * QBLK + row;
;       const u32x4 ov = *(const u32x4*)(Ost + row * RS + cc * 16); const u32x4 gv = *(const u32x4*)(gate + orow * NZ + cc * 8);
;       u32x4 w; w.x = cvt_pk_bf16(bf_lo(ov.x) * bf_lo(gv.x), bf_hi(ov.x) * bf_hi(gv.x)); w.y = cvt_pk_bf16(bf_lo(ov.y) * bf_lo(gv.y), bf_hi(ov.y) * bf_hi(gv.y));
;       w.z = cvt_pk_bf16(bf_lo(ov.z) * bf_lo(gv.z), bf_hi(ov.z) * bf_hi(gv.z)); w.w = cvt_pk_bf16(bf_lo(ov.w) * bf_lo(gv.w), bf_hi(ov.w) * bf_hi(gv.w));
;       *(u32x4*)(Yo + orow * 4096 + cc * 8) = w; }
;   }
;   __syncthreads();
	v_mov_b32_e32 v14, v46
	v_mov_b32_e32 v15, v47
	v_mov_b32_e32 v16, v48
	v_mov_b32_e32 v17, v49
	v_lshlrev_b32_e32 v20, 16, v14
	v_and_b32_e32 v14, 0xffff0000, v14
	v_lshlrev_b32_e32 v21, 16, v15
	v_and_b32_e32 v15, 0xffff0000, v15
	v_lshlrev_b32_e32 v23, 16, v16
	v_and_b32_e32 v16, 0xffff0000, v16
	v_lshlrev_b32_e32 v25, 16, v17
	v_and_b32_e32 v17, 0xffff0000, v17
	v_mul_f32_e32 v9, v14, v9
	v_mul_f32_e32 v14, v21, v10
	v_mul_f32_e32 v11, v15, v11
	v_mul_f32_e32 v12, v23, v12
	v_mul_f32_e32 v13, v16, v13
	v_mul_f32_e32 v15, v25, v18
	v_mul_f32_e32 v16, v17, v19
	v_mul_f32_e32 v5, v20, v5
	v_cvt_pk_bf16_f32 v10, v5, v9
	v_cvt_pk_bf16_f32 v11, v14, v11
	v_cvt_pk_bf16_f32 v12, v12, v13
	v_cvt_pk_bf16_f32 v13, v15, v16
	ds_read_b128 v[18:21], v8 offset:5440
	v_ashrrev_i32_e32 v23, 31, v22
	v_lshlrev_b64 v[22:23], 13, v[22:23]
	v_lshl_add_u64 v[22:23], v[6:7], 0, v[22:23]
	global_store_dwordx4 v[22:23], v[10:13], off offset:2048
	s_waitcnt lgkmcnt(0)
	v_lshlrev_b32_e32 v5, 16, v18
	v_and_b32_e32 v9, 0xffff0000, v18
	v_lshlrev_b32_e32 v10, 16, v19
	v_and_b32_e32 v11, 0xffff0000, v19
	v_lshlrev_b32_e32 v12, 16, v20
	v_and_b32_e32 v13, 0xffff0000, v20
	v_lshlrev_b32_e32 v18, 16, v21
	v_and_b32_e32 v19, 0xffff0000, v21
	v_mad_i64_i32 v[28:29], s[6:7], v26, s42, v[2:3]
	v_ashrrev_i32_e32 v25, 31, v24
	s_waitcnt vmcnt(7)
	v_mov_b32_e32 v14, v50
	v_mov_b32_e32 v15, v51
	v_mov_b32_e32 v16, v52
	v_mov_b32_e32 v17, v53
	v_lshlrev_b32_e32 v20, 16, v14
	v_and_b32_e32 v14, 0xffff0000, v14
	v_lshlrev_b32_e32 v21, 16, v15
	v_and_b32_e32 v15, 0xffff0000, v15
	v_lshlrev_b32_e32 v22, 16, v16
	v_and_b32_e32 v16, 0xffff0000, v16
	v_lshlrev_b32_e32 v23, 16, v17
	v_and_b32_e32 v17, 0xffff0000, v17
	v_mul_f32_e32 v9, v14, v9
	v_mul_f32_e32 v14, v21, v10
	v_mul_f32_e32 v11, v15, v11
	v_mul_f32_e32 v12, v22, v12
	v_mul_f32_e32 v13, v16, v13
	v_mul_f32_e32 v15, v23, v18
	v_mul_f32_e32 v16, v17, v19
	v_mul_f32_e32 v5, v20, v5
	v_cvt_pk_bf16_f32 v10, v5, v9
	v_cvt_pk_bf16_f32 v11, v14, v11
	v_cvt_pk_bf16_f32 v12, v12, v13
	v_cvt_pk_bf16_f32 v13, v15, v16
	ds_read_b128 v[18:21], v8 offset:6528
	v_or_b32_e32 v22, 28, v4
	v_lshlrev_b64 v[4:5], 13, v[24:25]
	v_mad_i64_i32 v[24:25], s[6:7], v22, s42, v[2:3]
	v_lshl_add_u64 v[2:3], v[6:7], 0, v[4:5]
	global_store_dwordx4 v[2:3], v[10:13], off offset:2048
	s_waitcnt lgkmcnt(0)
	v_lshlrev_b32_e32 v2, 16, v18
	v_and_b32_e32 v3, 0xffff0000, v18
	v_lshlrev_b32_e32 v4, 16, v19
	v_and_b32_e32 v5, 0xffff0000, v19
	v_lshlrev_b32_e32 v9, 16, v20
	v_and_b32_e32 v10, 0xffff0000, v20
	v_lshlrev_b32_e32 v11, 16, v21
	v_and_b32_e32 v12, 0xffff0000, v21
	v_ashrrev_i32_e32 v23, 31, v22
	s_mul_i32 s6, s12, s56
	s_add_i32 s10, s6, s2
	s_cmp_ge_i32 s10, s38
	s_waitcnt vmcnt(7)
	v_mov_b32_e32 v14, v54
	v_mov_b32_e32 v15, v55
	v_mov_b32_e32 v16, v56
	v_mov_b32_e32 v17, v57
	v_lshlrev_b32_e32 v13, 16, v14
	v_and_b32_e32 v14, 0xffff0000, v14
	v_lshlrev_b32_e32 v18, 16, v15
	v_and_b32_e32 v15, 0xffff0000, v15
	v_lshlrev_b32_e32 v19, 16, v16
	v_and_b32_e32 v16, 0xffff0000, v16
	v_lshlrev_b32_e32 v20, 16, v17
	v_and_b32_e32 v17, 0xffff0000, v17
	v_mul_f32_e32 v2, v13, v2
	v_mul_f32_e32 v3, v14, v3
	v_mul_f32_e32 v4, v18, v4
	v_mul_f32_e32 v5, v15, v5
	v_mul_f32_e32 v10, v16, v10
	v_mul_f32_e32 v11, v20, v11
	v_mul_f32_e32 v12, v17, v12
	v_mul_f32_e32 v9, v19, v9
	v_cvt_pk_bf16_f32 v2, v2, v3
	v_cvt_pk_bf16_f32 v3, v4, v5
	v_cvt_pk_bf16_f32 v4, v9, v10
	v_cvt_pk_bf16_f32 v5, v11, v12
	v_lshlrev_b64 v[14:15], 13, v[26:27]
	v_lshl_add_u64 v[20:21], v[6:7], 0, v[14:15]
	ds_read_b128 v[14:17], v8 offset:7616
	v_lshlrev_b64 v[18:19], 13, v[22:23]
	global_store_dwordx4 v[20:21], v[2:5], off offset:2048
	v_lshl_add_u64 v[6:7], v[6:7], 0, v[18:19]
	s_waitcnt lgkmcnt(0)
	v_lshlrev_b32_e32 v8, 16, v16
	v_lshlrev_b32_e32 v2, 16, v14
	v_and_b32_e32 v3, 0xffff0000, v14
	v_lshlrev_b32_e32 v4, 16, v15
	v_and_b32_e32 v5, 0xffff0000, v15
	v_and_b32_e32 v9, 0xffff0000, v16
	v_lshlrev_b32_e32 v14, 16, v17
	v_and_b32_e32 v15, 0xffff0000, v17
	s_waitcnt vmcnt(7)
	v_mov_b32_e32 v10, v58
	v_mov_b32_e32 v11, v59
	v_mov_b32_e32 v12, v60
	v_mov_b32_e32 v13, v61
	v_lshlrev_b32_e32 v16, 16, v10
	v_and_b32_e32 v10, 0xffff0000, v10
	v_lshlrev_b32_e32 v17, 16, v11
	v_and_b32_e32 v11, 0xffff0000, v11
	v_lshlrev_b32_e32 v18, 16, v12
	v_and_b32_e32 v12, 0xffff0000, v12
	v_lshlrev_b32_e32 v19, 16, v13
	v_and_b32_e32 v13, 0xffff0000, v13
	v_mul_f32_e32 v2, v16, v2
	v_mul_f32_e32 v3, v10, v3
	v_mul_f32_e32 v4, v17, v4
	v_mul_f32_e32 v5, v11, v5
	v_mul_f32_e32 v8, v18, v8
	v_mul_f32_e32 v9, v12, v9
	v_mul_f32_e32 v10, v19, v14
	v_mul_f32_e32 v11, v13, v15
	v_cvt_pk_bf16_f32 v2, v2, v3
	v_cvt_pk_bf16_f32 v3, v4, v5
	v_cvt_pk_bf16_f32 v4, v8, v9
	v_cvt_pk_bf16_f32 v5, v10, v11
	global_store_dwordx4 v[6:7], v[2:5], off offset:2048
	s_barrier
	s_cbranch_scc1 .LBB0_871

; __device__ __forceinline__ unsigned cvt_pk_bf16(float lo, float hi) { unsigned r; asm volatile("v_cvt_pk_bf16_f32 %0, %1, %2" : "=v"(r) : "v"(lo), "v"(hi)); return r; }
; __device__ __forceinline__ void attn_unit_dma(const bf16_t* __restrict__ Qb, const bf16_t* __restrict__ Kh, const bf16_t* __restrict__ Vh, int seq, char* lds, LAS unsigned char* ldsl, ...
;     ...
;       for (int e = 0; e < 8; ++e) { const f32x2 cs = tok0 < 0 ? (f32x2){1.f, 0.f} : *(const f32x2*)(rope + ((size_t)pos * 16 + hi * 8 + e) * 2);
;         const float y1 = x1[e] * rstd * gq[128 + 32 * ax + hi * 8 + e], y2 = x2[e] * rstd * gq[144 + 32 * ax + hi * 8 + e];
;         o1[e] = y1 * cs.x - y2 * cs.y; o2[e] = y1 * cs.y + y2 * cs.x; }
;       u32x4 a, b; a.x = cvt_pk_bf16(o1[0], o1[1]); a.y = cvt_pk_bf16(o1[2], o1[3]); a.z = cvt_pk_bf16(o1[4], o1[5]); a.w = cvt_pk_bf16(o1[6], o1[7]);
;       b.x = cvt_pk_bf16(o2[0], o2[1]); b.y = cvt_pk_bf16(o2[2], o2[3]); b.z = cvt_pk_bf16(o2[4], o2[5]); b.w = cvt_pk_bf16(o2[6], o2[7]);
;       qr[8 + 2 * ax] = *reinterpret_cast<const bf16x8*>(&a); qr[9 + 2 * ax] = *reinterpret_cast<const bf16x8*>(&b); }
.LBB0_833:
	s_nop 0
	global_load_dword v72, v[2:3], off offset:536
	global_load_dword v71, v[2:3], off offset:600
	global_load_dword v250, v[2:3], off offset:540
	global_load_dword v251, v[2:3], off offset:604
	s_and_b64 vcc, exec, s[6:7]
	s_cbranch_vccnz .LBB0_835
	v_lshl_add_u64 v[4:5], v[4:5], 3, s[18:19]
	global_load_dwordx2 v[22:23], v[4:5], off offset:56
.LBB0_835:
	v_mul_f32_e32 v5, v12, v59
	v_mul_f32_e32 v4, v12, v57
	s_waitcnt vmcnt(0)
	v_mul_f32_e32 v5, v5, v71
	v_mul_f32_e32 v4, v4, v72
	v_mul_f32_e32 v57, v33, v5
	v_fma_f32 v57, v32, v4, -v57
	v_mul_f32_e32 v32, v32, v5
	v_mul_f32_e32 v5, v12, v58
	v_fmac_f32_e32 v32, v33, v4
	v_mul_f32_e32 v4, v12, v55
	v_mul_f32_e32 v5, v5, v69
	v_mul_f32_e32 v4, v4, v70
	v_mul_f32_e32 v33, v31, v5
	v_fma_f32 v33, v30, v4, -v33
	v_mul_f32_e32 v30, v30, v5
	v_mul_f32_e32 v5, v12, v56
	v_fmac_f32_e32 v30, v31, v4
	v_mul_f32_e32 v4, v12, v53
	v_mul_f32_e32 v5, v5, v67
	v_mul_f32_e32 v4, v4, v68
	v_mul_f32_e32 v31, v29, v5
	v_fma_f32 v31, v28, v4, -v31
	v_mul_f32_e32 v28, v28, v5
	v_mul_f32_e32 v5, v12, v54
	v_fmac_f32_e32 v28, v29, v4
	v_mul_f32_e32 v4, v12, v51
	v_mul_f32_e32 v5, v5, v65
	v_mul_f32_e32 v4, v4, v66
	v_mul_f32_e32 v29, v27, v5
	v_fma_f32 v29, v26, v4, -v29
	v_mul_f32_e32 v26, v26, v5
	v_mul_f32_e32 v5, v12, v52
	v_fmac_f32_e32 v26, v27, v4
	v_mul_f32_e32 v4, v12, v49
	v_mul_f32_e32 v5, v5, v63
	v_mul_f32_e32 v4, v4, v64
	v_mul_f32_e32 v27, v25, v5
	v_fma_f32 v27, v24, v4, -v27
	v_mul_f32_e32 v24, v24, v5
	v_mul_f32_e32 v5, v12, v50
	v_fmac_f32_e32 v24, v25, v4
	v_mul_f32_e32 v4, v12, v47
	v_mul_f32_e32 v5, v5, v61
	v_mul_f32_e32 v4, v4, v62
	v_mul_f32_e32 v25, v7, v5
	v_mul_f32_e32 v47, v6, v5
	v_mul_f32_e32 v5, v12, v48
	v_fma_f32 v25, v6, v4, -v25
	v_fmac_f32_e32 v47, v7, v4
	v_mul_f32_e32 v4, v12, v46
	v_mul_f32_e32 v5, v5, v16
	v_mul_f32_e32 v4, v4, v60
	v_mul_f32_e32 v6, v9, v5
	v_fma_f32 v16, v8, v4, -v6
	v_mov_b32_e32 v7, v250
	v_mov_b32_e32 v6, v251
	v_mul_f32_e32 v8, v8, v5
	v_fmac_f32_e32 v8, v9, v4
	v_pk_mul_f32 v[4:5], v[12:13], v[20:21] op_sel_hi:[0,1]
	v_cvt_pk_bf16_f32 v152, v16, v25
	v_cvt_pk_bf16_f32 v153, v27, v29
	v_cvt_pk_bf16_f32 v154, v31, v33
	s_and_b64 vcc, exec, s[6:7]
	s_waitcnt vmcnt(0)
	v_pk_mul_f32 v[4:5], v[4:5], v[6:7]
	s_nop 0
	v_pk_mul_f32 v[6:7], v[22:23], v[4:5] op_sel:[0,1] op_sel_hi:[1,0]
	v_pk_mul_f32 v[4:5], v[22:23], v[4:5]
	v_sub_f32_e32 v6, v6, v7
	v_add_f32_e32 v4, v5, v4
	v_cvt_pk_bf16_f32 v155, v57, v6
	v_cvt_pk_bf16_f32 v148, v8, v47
	v_cvt_pk_bf16_f32 v149, v24, v26
	v_cvt_pk_bf16_f32 v150, v28, v30
	v_cvt_pk_bf16_f32 v151, v32, v4
	v_lshlrev_b32_e32 v4, 4, v13
	v_and_b32_e32 v4, 0x3f0, v4
	v_cndmask_b32_e64 v6, v4, 0, s[10:11]
	v_mov_b32_e32 v5, 0
	v_mov_b32_e32 v4, 1.0
	v_or_b32_e32 v13, v6, v36
	v_mov_b32_e32 v6, 1.0
	v_mov_b32_e32 v7, 0
	s_cbranch_vccnz .LBB0_837
	v_lshlrev_b32_e32 v6, 3, v13
	global_load_dwordx2 v[6:7], v6, s[18:19]
